# PRE: load bursts removed: S0 lora-fragment loads spread through S0 (store-drain waits dropped), next-item prefetch loads (12) spread over S2..S4 with zero-page addressing instead of EXEC masking
# speedup vs baseline: 1.0109x; 1.0017x over previous
.LBB0_62:
	s_or_b64 exec, exec, s[24:25]
	v_mov_b32_e32 v3, v180
	s_waitcnt lgkmcnt(0)
	s_barrier
	v_readlane_b32 s0, v252, 18
	v_add_u32_e32 v1, s42, v3
	v_ashrrev_i32_e32 v1, 3, v1
	v_add_u32_e32 v1, s0, v1
	v_readlane_b32 s0, v252, 19
	v_lshlrev_b32_e32 v3, 3, v3
	s_waitcnt lgkmcnt(0)
	s_mov_b64 s[98:99], s[30:31]
	s_add_u32 s24, s30, 0x7c00000
	v_add_u32_e32 v2, s0, v1
	v_and_b32_e32 v8, 56, v3
	v_ashrrev_i32_e32 v3, 31, v2
	s_addc_u32 s25, s31, 0
	v_lshlrev_b64 v[4:5], 9, v[2:3]
	v_writelane_b32 v255, s24, 3
	v_lshlrev_b32_e32 v6, 1, v8
	v_mov_b32_e32 v7, v0
	v_lshl_add_u64 v[2:3], s[24:25], 0, v[4:5]
	v_lshl_add_u64 v[6:7], v[2:3], 0, v[6:7]
	global_load_dwordx4 v[100:103], v[6:7], off
	v_mov_b32_e32 v106, v0
	v_mov_b32_e32 v107, v0
	v_mov_b32_e32 v104, v0
	v_mov_b32_e32 v105, v0
	v_mov_b64_e32 v[110:111], v[106:107]
	v_writelane_b32 v255, s25, 4
	v_cmp_lt_i32_e32 vcc, 0, v1
	v_mov_b64_e32 v[108:109], v[104:105]
	s_and_saveexec_b64 s[26:27], vcc
	s_cbranch_execz .LBB0_64
	global_load_dwordx4 v[108:111], v[6:7], off offset:-512

.LBB0_81:
	v_mov_b32_e32 v1, v180
	v_mov_b32_e32 v48, v180
	v_add_lshl_u32 v240, s77, v1, 4
	s_nop 0
	v_lshlrev_b32_e32 v45, 16, v104
	v_and_b32_e32 v49, 7, v48
	v_lshlrev_b32_e32 v50, 5, v49
	v_add_u32_e32 v51, 0, v50
	v_add_u32_e32 v2, 0x25400, v51
	v_add_u32_e32 v3, 0x25600, v51
	ds_read_b128 v[28:31], v2
	ds_read_b128 v[32:35], v2 offset:16
	ds_read_b128 v[36:39], v3
	ds_read_b128 v[40:43], v3 offset:16
	v_lshlrev_b32_e32 v2, 16, v100
	v_lshlrev_b32_e32 v44, 16, v108
	v_pk_add_f32 v[44:45], v[44:45], v[2:3] op_sel_hi:[1,0] neg_lo:[0,1] neg_hi:[0,1]
	s_waitcnt lgkmcnt(3)
	global_load_dwordx4 v[20:23], v240, s[54:55]
	v_mov_b32_e32 v46, v28
	s_waitcnt lgkmcnt(1)
	v_mov_b32_e32 v47, v36
	v_pk_mul_f32 v[44:45], v[44:45], v[46:47]
	v_mov_b32_e32 v36, v29
	v_add_f32_e32 v2, v44, v2
	v_add_f32_e32 v3, v2, v45
	v_and_b32_e32 v2, 0xffff0000, v100
	v_and_b32_e32 v45, 0xffff0000, v104
	v_and_b32_e32 v44, 0xffff0000, v108
	v_pk_add_f32 v[44:45], v[44:45], v[2:3] op_sel_hi:[1,0] neg_lo:[0,1] neg_hi:[0,1]
	v_add_u32_e32 v1, s42, v48
	v_pk_mul_f32 v[28:29], v[44:45], v[36:37]
	v_mov_b32_e32 v36, v30
	v_add_f32_e32 v2, v28, v2
	v_add_f32_e32 v44, v2, v29
	v_lshlrev_b32_e32 v2, 16, v101
	v_lshlrev_b32_e32 v29, 16, v105
	v_lshlrev_b32_e32 v28, 16, v109
	v_pk_add_f32 v[28:29], v[28:29], v[2:3] op_sel_hi:[1,0] neg_lo:[0,1] neg_hi:[0,1]
	v_mov_b32_e32 v37, v38
	v_pk_mul_f32 v[28:29], v[28:29], v[36:37]
	v_mov_b32_e32 v38, v31
	v_add_f32_e32 v2, v28, v2
	v_add_f32_e32 v36, v2, v29
	v_and_b32_e32 v2, 0xffff0000, v101
	v_and_b32_e32 v29, 0xffff0000, v105
	v_and_b32_e32 v28, 0xffff0000, v109
	v_pk_add_f32 v[28:29], v[28:29], v[2:3] op_sel_hi:[1,0] neg_lo:[0,1] neg_hi:[0,1]
	v_mov_b32_e32 v30, v32
	v_pk_mul_f32 v[28:29], v[28:29], v[38:39]
	s_waitcnt lgkmcnt(0)
	v_mov_b32_e32 v31, v40
	v_add_f32_e32 v2, v28, v2
	v_add_f32_e32 v37, v2, v29
	v_lshlrev_b32_e32 v2, 16, v102
	v_lshlrev_b32_e32 v29, 16, v106
	v_lshlrev_b32_e32 v28, 16, v110
	v_pk_add_f32 v[28:29], v[28:29], v[2:3] op_sel_hi:[1,0] neg_lo:[0,1] neg_hi:[0,1]
	v_mov_b32_e32 v40, v33
	v_pk_mul_f32 v[28:29], v[28:29], v[30:31]
	v_mov_b32_e32 v30, v34
	v_add_f32_e32 v2, v28, v2
	v_add_f32_e32 v32, v2, v29
	v_and_b32_e32 v2, 0xffff0000, v102
	global_load_dwordx4 v[24:27], v240, s[58:59]
	v_and_b32_e32 v29, 0xffff0000, v106
	v_and_b32_e32 v28, 0xffff0000, v110
	v_pk_add_f32 v[28:29], v[28:29], v[2:3] op_sel_hi:[1,0] neg_lo:[0,1] neg_hi:[0,1]
	v_mov_b32_e32 v31, v42
	v_pk_mul_f32 v[28:29], v[28:29], v[40:41]
	v_mov_b32_e32 v42, v35
	v_add_f32_e32 v2, v28, v2
	v_add_f32_e32 v33, v2, v29
	v_lshlrev_b32_e32 v2, 16, v103
	v_lshlrev_b32_e32 v29, 16, v107
	v_lshlrev_b32_e32 v28, 16, v111
	v_pk_add_f32 v[28:29], v[28:29], v[2:3] op_sel_hi:[1,0] neg_lo:[0,1] neg_hi:[0,1]
	v_ashrrev_i32_e32 v1, 3, v1
	v_pk_mul_f32 v[28:29], v[28:29], v[30:31]
	v_add_f32_e32 v30, v44, v44
	v_add_f32_e32 v2, v28, v2
	v_add_f32_e32 v34, v2, v29
	v_and_b32_e32 v2, 0xffff0000, v103
	v_and_b32_e32 v29, 0xffff0000, v107
	v_and_b32_e32 v28, 0xffff0000, v111
	v_pk_add_f32 v[28:29], v[28:29], v[2:3] op_sel_hi:[1,0] neg_lo:[0,1] neg_hi:[0,1]
	v_add_f32_e32 v3, v3, v3
	v_mul_f32_e32 v3, 0x3fb8aa3b, v3
	v_exp_f32_e32 v3, v3
	v_mul_f32_e32 v30, 0x3fb8aa3b, v30
	v_exp_f32_e32 v31, v30
	v_pk_mul_f32 v[28:29], v[28:29], v[42:43]
	v_add_f32_e32 v3, 1.0, v3
	v_rcp_f32_e32 v30, v3
	v_add_f32_e32 v3, 1.0, v31
	v_rcp_f32_e32 v31, v3
	v_add_f32_e32 v2, v28, v2
	v_add_f32_e32 v28, v36, v36
	v_mul_f32_e32 v28, 0x3fb8aa3b, v28
	v_add_f32_e32 v29, v2, v29
	v_pk_fma_f32 v[2:3], v[30:31], 2.0, 1.0 op_sel_hi:[1,0,0] neg_lo:[1,0,0] neg_hi:[1,0,0]
	v_exp_f32_e32 v30, v28
	v_add_f32_e32 v28, v37, v37
	v_mul_f32_e32 v28, 0x3fb8aa3b, v28
	v_exp_f32_e32 v31, v28
	v_cvt_pk_bf16_f32 v28, v2, v3
	v_add_f32_e32 v2, 1.0, v30
	v_add_f32_e32 v30, v32, v32
	v_add_f32_e32 v3, 1.0, v31
	v_add_f32_e32 v31, v33, v33
	global_load_dwordx4 v[60:63], v240, s[54:55] offset:1024
	v_mul_f32_e32 v30, 0x3fb8aa3b, v30
	v_mul_f32_e32 v31, 0x3fb8aa3b, v31
	v_add_f32_e32 v32, v34, v34
	v_add_f32_e32 v29, v29, v29
	v_exp_f32_e32 v30, v30
	v_exp_f32_e32 v31, v31
	v_mul_f32_e32 v32, 0x3fb8aa3b, v32
	v_mul_f32_e32 v29, 0x3fb8aa3b, v29
	v_exp_f32_e32 v32, v32
	v_exp_f32_e32 v29, v29
	v_rcp_f32_e32 v2, v2
	v_rcp_f32_e32 v3, v3
	v_add_f32_e32 v30, 1.0, v30
	v_add_f32_e32 v31, 1.0, v31
	v_rcp_f32_e32 v30, v30
	v_rcp_f32_e32 v31, v31
	v_add_f32_e32 v32, 1.0, v32
	v_add_f32_e32 v29, 1.0, v29
	v_rcp_f32_e32 v32, v32
	v_rcp_f32_e32 v33, v29
	v_pk_fma_f32 v[2:3], v[2:3], 2.0, 1.0 op_sel_hi:[1,0,0] neg_lo:[1,0,0] neg_hi:[1,0,0]
	v_mul_lo_u32 v76, v1, s64
	v_cvt_pk_bf16_f32 v29, v2, v3
	v_pk_fma_f32 v[2:3], v[30:31], 2.0, 1.0 op_sel_hi:[1,0,0] neg_lo:[1,0,0] neg_hi:[1,0,0]
	v_lshlrev_b32_e32 v77, 4, v49
	v_cvt_pk_bf16_f32 v30, v2, v3
	v_pk_fma_f32 v[2:3], v[32:33], 2.0, 1.0 op_sel_hi:[1,0,0] neg_lo:[1,0,0] neg_hi:[1,0,0]
	v_readlane_b32 s27, v253, 61
	v_cvt_pk_bf16_f32 v31, v2, v3
	v_add_u32_e32 v3, 0x25700, v51
	v_add3_u32 v2, s27, v76, v77
	ds_write_b128 v2, v[28:31]
	v_add_u32_e32 v2, 0x25500, v51
	global_load_dwordx4 v[56:59], v240, s[58:59] offset:1024
	ds_read_b128 v[28:31], v2
	ds_read_b128 v[32:35], v2 offset:16
	ds_read_b128 v[36:39], v3
	ds_read_b128 v[40:43], v3 offset:16
	s_nop 0
	v_lshlrev_b32_e32 v2, 16, v112
	v_and_b32_e32 v3, 0xffff0000, v112
	v_lshlrev_b32_e32 v44, 16, v116
	v_and_b32_e32 v45, 0xffff0000, v116
	v_lshlrev_b32_e32 v46, 16, v120
	v_and_b32_e32 v47, 0xffff0000, v120
	v_pk_add_f32 v[44:45], v[44:45], v[2:3] neg_lo:[0,1] neg_hi:[0,1]
	v_readlane_b32 s27, v253, 62
	s_waitcnt lgkmcnt(3)
	v_pk_fma_f32 v[28:29], v[44:45], v[28:29], v[2:3]
	v_pk_add_f32 v[2:3], v[46:47], v[2:3] neg_lo:[0,1] neg_hi:[0,1]
	v_lshlrev_b32_e32 v44, 16, v121
	s_waitcnt lgkmcnt(1)
	v_pk_fma_f32 v[2:3], v[2:3], v[36:37], v[28:29]
	v_lshlrev_b32_e32 v28, 16, v113
	v_and_b32_e32 v29, 0xffff0000, v113
	v_lshlrev_b32_e32 v36, 16, v117
	v_and_b32_e32 v37, 0xffff0000, v117
	v_and_b32_e32 v45, 0xffff0000, v121
	v_pk_add_f32 v[36:37], v[36:37], v[28:29] neg_lo:[0,1] neg_hi:[0,1]
	s_nop 0
	v_lshlrev_b32_e32 v46, 16, v144
	v_pk_fma_f32 v[30:31], v[36:37], v[30:31], v[28:29]
	v_pk_add_f32 v[28:29], v[44:45], v[28:29] neg_lo:[0,1] neg_hi:[0,1]
	v_lshlrev_b32_e32 v36, 16, v118
	v_pk_fma_f32 v[30:31], v[28:29], v[38:39], v[30:31]
	v_lshlrev_b32_e32 v28, 16, v114
	global_load_dwordx4 v[72:75], v240, s[54:55] offset:2048
	v_and_b32_e32 v29, 0xffff0000, v114
	v_and_b32_e32 v37, 0xffff0000, v118
	v_lshlrev_b32_e32 v38, 16, v122
	v_and_b32_e32 v39, 0xffff0000, v122
	v_pk_add_f32 v[36:37], v[36:37], v[28:29] neg_lo:[0,1] neg_hi:[0,1]
	v_lshlrev_b32_e32 v44, 16, v140
	v_pk_fma_f32 v[32:33], v[36:37], v[32:33], v[28:29]
	v_pk_add_f32 v[28:29], v[38:39], v[28:29] neg_lo:[0,1] neg_hi:[0,1]
	v_lshlrev_b32_e32 v36, 16, v119
	v_and_b32_e32 v37, 0xffff0000, v119
	v_lshlrev_b32_e32 v38, 16, v115
	v_and_b32_e32 v39, 0xffff0000, v115
	s_waitcnt lgkmcnt(0)
	v_pk_fma_f32 v[32:33], v[28:29], v[40:41], v[32:33]
	v_lshlrev_b32_e32 v28, 16, v123
	v_and_b32_e32 v29, 0xffff0000, v123
	v_pk_add_f32 v[36:37], v[36:37], v[38:39] neg_lo:[0,1] neg_hi:[0,1]
	v_pk_add_f32 v[28:29], v[28:29], v[38:39] neg_lo:[0,1] neg_hi:[0,1]
	v_pk_fma_f32 v[34:35], v[36:37], v[34:35], v[38:39]
	v_and_b32_e32 v45, 0xffff0000, v140
	v_pk_fma_f32 v[34:35], v[28:29], v[42:43], v[34:35]
	v_cvt_pk_bf16_f32 v28, v2, v3
	v_cvt_pk_bf16_f32 v29, v30, v31
	v_cvt_pk_bf16_f32 v30, v32, v33
	v_cvt_pk_bf16_f32 v31, v34, v35
	v_add3_u32 v2, s27, v76, v77
	ds_write_b128 v2, v[28:31]
	v_add_u32_e32 v2, 0x24e00, v51
	v_add_u32_e32 v3, 0x24f00, v51
	ds_read_b128 v[28:31], v2
	ds_read_b128 v[32:35], v2 offset:16
	ds_read_b128 v[36:39], v3
	ds_read_b128 v[40:43], v3 offset:16
	v_lshlrev_b32_e32 v2, 16, v136
	v_and_b32_e32 v3, 0xffff0000, v136
	v_and_b32_e32 v47, 0xffff0000, v144
	v_pk_add_f32 v[44:45], v[44:45], v[2:3] neg_lo:[0,1] neg_hi:[0,1]
	v_cmp_gt_i32_e32 vcc, 32, v1
	s_waitcnt lgkmcnt(3)
	v_pk_fma_f32 v[28:29], v[44:45], v[28:29], v[2:3]
	v_pk_add_f32 v[2:3], v[46:47], v[2:3] neg_lo:[0,1] neg_hi:[0,1]
	v_lshlrev_b32_e32 v44, 16, v145
	s_waitcnt lgkmcnt(1)
	v_pk_fma_f32 v[28:29], v[2:3], v[36:37], v[28:29]
	v_lshlrev_b32_e32 v2, 16, v137
	global_load_dwordx4 v[64:67], v240, s[58:59] offset:2048
	v_and_b32_e32 v3, 0xffff0000, v137
	v_lshlrev_b32_e32 v36, 16, v141
	v_and_b32_e32 v37, 0xffff0000, v141
	v_and_b32_e32 v45, 0xffff0000, v145
	v_pk_add_f32 v[36:37], v[36:37], v[2:3] neg_lo:[0,1] neg_hi:[0,1]
	v_lshlrev_b32_e32 v46, 16, v132
	v_pk_fma_f32 v[30:31], v[36:37], v[30:31], v[2:3]
	v_pk_add_f32 v[2:3], v[44:45], v[2:3] neg_lo:[0,1] neg_hi:[0,1]
	v_lshlrev_b32_e32 v36, 16, v142
	v_pk_fma_f32 v[30:31], v[2:3], v[38:39], v[30:31]
	v_lshlrev_b32_e32 v2, 16, v138
	v_and_b32_e32 v3, 0xffff0000, v138
	v_and_b32_e32 v37, 0xffff0000, v142
	v_lshlrev_b32_e32 v38, 16, v146
	v_and_b32_e32 v39, 0xffff0000, v146
	v_pk_add_f32 v[36:37], v[36:37], v[2:3] neg_lo:[0,1] neg_hi:[0,1]
	v_lshlrev_b32_e32 v44, 16, v128
	v_pk_fma_f32 v[32:33], v[36:37], v[32:33], v[2:3]
	v_pk_add_f32 v[2:3], v[38:39], v[2:3] neg_lo:[0,1] neg_hi:[0,1]
	v_lshlrev_b32_e32 v36, 16, v143
	v_and_b32_e32 v37, 0xffff0000, v143
	v_lshlrev_b32_e32 v38, 16, v139
	v_and_b32_e32 v39, 0xffff0000, v139
	s_waitcnt lgkmcnt(0)
	v_pk_fma_f32 v[32:33], v[2:3], v[40:41], v[32:33]
	v_lshlrev_b32_e32 v2, 16, v147
	v_and_b32_e32 v3, 0xffff0000, v147
	v_pk_add_f32 v[36:37], v[36:37], v[38:39] neg_lo:[0,1] neg_hi:[0,1]
	v_pk_add_f32 v[2:3], v[2:3], v[38:39] neg_lo:[0,1] neg_hi:[0,1]
	v_pk_fma_f32 v[34:35], v[36:37], v[34:35], v[38:39]
	v_and_b32_e32 v45, 0xffff0000, v128
	v_pk_fma_f32 v[34:35], v[2:3], v[42:43], v[34:35]
	v_mov_b32_e32 v2, 0x1d400
	v_mov_b32_e32 v3, 0xd800
	v_cndmask_b32_e32 v2, v2, v3, vcc
	v_lshlrev_b32_e32 v3, 8, v1
	v_add_u32_e32 v2, 0, v2
	v_and_b32_e32 v3, 0x1f00, v3
	v_add3_u32 v2, v2, v3, v50
	ds_write_b128 v2, v[28:31]
	ds_write_b128 v2, v[32:35] offset:16
	v_add_u32_e32 v2, 0x25000, v51
	v_add_u32_e32 v3, 0x25100, v51
	ds_read_b128 v[28:31], v2
	ds_read_b128 v[32:35], v2 offset:16
	global_load_dwordx4 v[68:71], v240, s[54:55] offset:3072
	ds_read_b128 v[36:39], v3
	ds_read_b128 v[40:43], v3 offset:16
	v_lshlrev_b32_e32 v2, 16, v124
	v_and_b32_e32 v3, 0xffff0000, v124
	v_and_b32_e32 v47, 0xffff0000, v132
	v_pk_add_f32 v[44:45], v[44:45], v[2:3] neg_lo:[0,1] neg_hi:[0,1]
	v_cmp_eq_u32_e32 vcc, 0, v49
	s_waitcnt lgkmcnt(3)
	v_pk_fma_f32 v[28:29], v[44:45], v[28:29], v[2:3]
	v_pk_add_f32 v[2:3], v[46:47], v[2:3] neg_lo:[0,1] neg_hi:[0,1]
	s_waitcnt lgkmcnt(1)
	v_pk_fma_f32 v[76:77], v[2:3], v[36:37], v[28:29]
	v_lshlrev_b32_e32 v2, 16, v125
	v_and_b32_e32 v3, 0xffff0000, v125
	v_lshlrev_b32_e32 v28, 16, v129
	v_and_b32_e32 v29, 0xffff0000, v129
	v_lshlrev_b32_e32 v36, 16, v133
	v_and_b32_e32 v37, 0xffff0000, v133
	v_pk_add_f32 v[28:29], v[28:29], v[2:3] neg_lo:[0,1] neg_hi:[0,1]
	s_nop 0
	v_pk_fma_f32 v[28:29], v[28:29], v[30:31], v[2:3]
	v_pk_add_f32 v[2:3], v[36:37], v[2:3] neg_lo:[0,1] neg_hi:[0,1]
	v_lshlrev_b32_e32 v30, 16, v134
	v_pk_fma_f32 v[78:79], v[2:3], v[38:39], v[28:29]
	v_lshlrev_b32_e32 v2, 16, v126
	v_and_b32_e32 v3, 0xffff0000, v126
	v_lshlrev_b32_e32 v28, 16, v130
	v_and_b32_e32 v29, 0xffff0000, v130
	v_and_b32_e32 v31, 0xffff0000, v134
	v_pk_add_f32 v[28:29], v[28:29], v[2:3] neg_lo:[0,1] neg_hi:[0,1]
	v_add_u32_e32 v38, 0x24700, v51
	v_pk_fma_f32 v[28:29], v[28:29], v[32:33], v[2:3]
	v_pk_add_f32 v[2:3], v[30:31], v[2:3] neg_lo:[0,1] neg_hi:[0,1]
	v_lshlrev_b32_e32 v32, 16, v127
	s_waitcnt lgkmcnt(0)
	v_pk_fma_f32 v[80:81], v[2:3], v[40:41], v[28:29]
	v_lshlrev_b32_e32 v28, 16, v131
	v_and_b32_e32 v29, 0xffff0000, v131
	v_and_b32_e32 v33, 0xffff0000, v127
	v_pk_add_f32 v[36:37], v[28:29], v[32:33] neg_lo:[0,1] neg_hi:[0,1]
	ds_read_b128 v[28:31], v38
	v_lshlrev_b32_e32 v2, 16, v135
	v_and_b32_e32 v3, 0xffff0000, v135
	v_pk_fma_f32 v[34:35], v[36:37], v[34:35], v[32:33]
	v_pk_add_f32 v[2:3], v[2:3], v[32:33] neg_lo:[0,1] neg_hi:[0,1]
	global_load_dwordx4 v[52:55], v240, s[58:59] offset:3072
	s_nop 0
	v_pk_fma_f32 v[82:83], v[2:3], v[42:43], v[34:35]
	ds_read_b128 v[32:35], v38 offset:16
	s_waitcnt lgkmcnt(1)
	v_mul_f32_e32 v3, v77, v29
	v_mul_f32_e32 v2, v76, v28
	v_mul_f32_e32 v3, v3, v3
	v_fmac_f32_e32 v3, v2, v2
	v_mul_f32_e32 v2, v78, v30
	v_fmac_f32_e32 v3, v2, v2
	v_mul_f32_e32 v2, v79, v31
	v_fmac_f32_e32 v3, v2, v2
	s_waitcnt lgkmcnt(0)
	v_mul_f32_e32 v2, v80, v32
	v_fmac_f32_e32 v3, v2, v2
	v_mul_f32_e32 v2, v81, v33
	v_fmac_f32_e32 v3, v2, v2
	v_mul_f32_e32 v2, v82, v34
	v_fmac_f32_e32 v3, v2, v2
	v_mul_f32_e32 v2, v83, v35
	v_lshlrev_b32_e32 v28, 2, v48
	v_fmac_f32_e32 v3, v2, v2
	v_xor_b32_e32 v2, 4, v28
	ds_bpermute_b32 v2, v2, v3
	s_waitcnt lgkmcnt(0)
	v_add_f32_e32 v2, v3, v2
	v_xor_b32_e32 v3, 8, v28
	ds_bpermute_b32 v3, v3, v2
	s_waitcnt lgkmcnt(0)
	v_add_f32_e32 v2, v2, v3
	v_xor_b32_e32 v3, 16, v28
	ds_bpermute_b32 v3, v3, v2
	s_and_saveexec_b64 s[30:31], vcc
	s_cbranch_execz .LBB0_83
	s_waitcnt lgkmcnt(0)
	v_add_f32_e32 v2, v2, v3
	v_add_f32_e32 v2, 0x2b8cbccc, v2
	s_mov_b32 s27, 0xf800000
	v_mul_f32_e32 v3, 0x4f800000, v2
	v_cmp_gt_f32_e32 vcc, s27, v2
	v_lshl_add_u32 v1, v1, 2, 0
	v_add_u32_e32 v1, 0x24000, v1
	v_cndmask_b32_e32 v2, v2, v3, vcc
	v_sqrt_f32_e32 v3, v2
	s_nop 0
	v_add_u32_e32 v28, -1, v3
	v_fma_f32 v30, -v28, v3, v2
	v_add_u32_e32 v29, 1, v3
	v_cmp_ge_f32_e64 s[38:39], 0, v30
	s_nop 1
	v_cndmask_b32_e64 v28, v3, v28, s[38:39]
	v_fma_f32 v3, -v29, v3, v2
	v_cmp_lt_f32_e64 s[38:39], 0, v3
	s_nop 1
	v_cndmask_b32_e64 v3, v28, v29, s[38:39]
	v_mul_f32_e32 v28, 0x37800000, v3
	v_cndmask_b32_e32 v3, v3, v28, vcc
	v_cmp_class_f32_e32 vcc, v2, v222
	s_nop 1
	v_cndmask_b32_e32 v2, v3, v2, vcc
	v_div_scale_f32 v3, s[38:39], v2, v2, 1.0
	v_rcp_f32_e32 v28, v3
	s_nop 0
	v_fma_f32 v29, -v3, v28, 1.0
	v_fmac_f32_e32 v28, v29, v28
	v_div_scale_f32 v29, vcc, 1.0, v2, 1.0
	v_mul_f32_e32 v30, v29, v28
	v_fma_f32 v31, -v3, v30, v29
	v_fmac_f32_e32 v30, v31, v28
	v_fma_f32 v3, -v3, v30, v29
	v_div_fmas_f32 v3, v3, v28, v30
	v_div_fixup_f32 v2, v3, v2, 1.0
	ds_write_b32 v1, v2
.LBB0_83:
	s_or_b64 exec, exec, s[30:31]
	v_mov_b32_e32 v1, v180
	s_waitcnt lgkmcnt(0)
	s_barrier
	v_readlane_b32 s27, v253, 61
	v_and_b32_e32 v2, 31, v1
	v_or_b32_e32 v156, s43, v2
	v_bitop3_b32 v2, v2, 63, s43 bitop3:0x36
	v_ashrrev_i32_e32 v1, 5, v1
	v_cndmask_b32_e64 v2, v2, v156, s[36:37]
	v_mul_u32_u24_e32 v2, 0x90, v2
	s_waitcnt lgkmcnt(0)
	v_lshlrev_b32_e32 v3, 4, v1
	v_readlane_b32 s30, v253, 62
	v_add3_u32 v32, s27, v2, v3
	ds_read_b128 v[28:31], v32
	ds_read_b128 v[84:87], v32 offset:32
	ds_read_b128 v[88:91], v32 offset:64
	ds_read_b128 v[92:95], v32 offset:96
	v_add3_u32 v2, s30, v2, v3
	ds_read_b128 v[32:35], v2
	ds_read_b128 v[96:99], v2 offset:32
	ds_read_b128 v[148:151], v2 offset:64
	ds_read_b128 v[152:155], v2 offset:96
	s_waitcnt vmcnt(7) lgkmcnt(7)
	v_mfma_f32_32x32x16_bf16 v[36:51], v[20:23], v[28:31], 0
	v_add_u32_e32 v2, s47, v3
	v_add_u32_e32 v3, s46, v3
	v_lshlrev_b32_e32 v1, 3, v1
	s_waitcnt vmcnt(6) lgkmcnt(3)
	v_mfma_f32_32x32x16_bf16 v[20:35], v[24:27], v[32:35], 0
	s_waitcnt vmcnt(5)
	v_mfma_f32_32x32x16_bf16 v[36:51], v[60:63], v[84:87], v[36:51]
	ds_read_b128 v[60:63], v2 offset:32
	s_waitcnt vmcnt(4) lgkmcnt(3)
	v_mfma_f32_32x32x16_bf16 v[20:35], v[56:59], v[96:99], v[20:35]
	ds_read_b128 v[56:59], v2
	v_mov_b32_e32 v98, s30
	v_mov_b32_e32 v99, s27
	s_waitcnt vmcnt(3)
	v_mfma_f32_32x32x16_bf16 v[36:51], v[72:75], v[88:91], v[36:51]
	v_mov_b32_e32 v90, s76
	v_mad_u32_u24 v90, v156, s64, v90
	v_add3_u32 v1, v90, v1, s28
	s_waitcnt vmcnt(2) lgkmcnt(3)
	v_mfma_f32_32x32x16_bf16 v[20:35], v[64:67], v[148:151], v[20:35]
	s_waitcnt vmcnt(1)
	v_mfma_f32_32x32x16_bf16 v[36:51], v[68:71], v[92:95], v[36:51]
	ds_read_b128 v[64:67], v3
	ds_read_b128 v[68:71], v3 offset:32
	s_waitcnt vmcnt(0) lgkmcnt(4)
	v_mfma_f32_32x32x16_bf16 v[20:35], v[52:55], v[152:155], v[20:35]
	v_readlane_b32 s101, v252, 21
	v_readlane_b32 s100, v252, 16
	v_add_u32_e32 v250, s42, v180
	v_mov_b32_e32 v251, s26
	v_ashrrev_i32_e32 v250, 3, v250
	v_and_b32_e32 v249, 0xfc0, v251
	v_and_b32_e32 v251, 0x7ffff000, v251
	v_add_u32_e32 v250, v249, v250
	v_add_u32_e32 v251, v251, v250
	v_and_b32_e32 v249, 7, v180
	v_lshlrev_b32_e32 v249, 4, v249
	v_lshlrev_b32_e32 v241, 9, v251
	v_lshlrev_b32_e32 v244, 10, v251
	v_add_u32_e32 v241, v241, v249
	v_add_u32_e32 v244, v244, v249
	v_lshl_add_u32 v244, s100, 1, v244
	v_add_u32_e32 v241, 0x7c00000, v241
	v_add_u32_e32 v247, 0x4c00000, v244
	v_add_u32_e32 v244, 0x5c00000, v244
	s_add_i32 s100, s50, 16
	s_cmp_lt_u32 s100, s101
	s_cselect_b64 s[100:101], -1, 0
	v_lshlrev_b32_e32 v251, 4, v180
	v_add_u32_e32 v242, 0xfffffe00, v241
	v_add_u32_e32 v243, 0x200, v241
	v_add_u32_e32 v245, 0xfffffc00, v244
	v_add_u32_e32 v246, 0x400, v244
	v_add_u32_e32 v248, 0xfffffc00, v247
	v_add_u32_e32 v249, 0x400, v247
	v_cndmask_b32_e64 v241, v251, v241, s[100:101]
	v_cndmask_b32_e64 v244, v251, v244, s[100:101]
	v_cndmask_b32_e64 v247, v251, v247, s[100:101]
	v_cmp_lt_i32_e32 vcc, 0, v250
	s_and_b64 vcc, vcc, s[100:101]
	s_nop 0
	v_cndmask_b32_e32 v242, v251, v242, vcc
	v_cndmask_b32_e32 v245, v251, v245, vcc
	v_cndmask_b32_e32 v248, v251, v248, vcc
	v_cmp_gt_i32_e32 vcc, 0xfff, v250
	s_and_b64 vcc, vcc, s[100:101]
	s_nop 0
	v_cndmask_b32_e32 v243, v251, v243, vcc
	v_cndmask_b32_e32 v246, v251, v246, vcc
	v_cndmask_b32_e32 v249, v251, v249, vcc
	s_waitcnt lgkmcnt(2)
	s_nop 6
	v_add_f32_e32 v36, v36, v56
	v_mul_f32_e32 v36, 0xbfb8aa3b, v36
	v_exp_f32_e32 v36, v36
	s_nop 0
	v_add_f32_e32 v36, 1.0, v36
	s_waitcnt lgkmcnt(1)
	v_add_f32_e32 v20, v20, v64
	v_mul_f32_e32 v20, 0xbfb8aa3b, v20
	v_rcp_f32_e32 v74, v36
	v_add_f32_e32 v36, v37, v57
	v_exp_f32_e32 v20, v20
	v_mul_f32_e32 v36, 0xbfb8aa3b, v36
	v_add_f32_e32 v21, v21, v65
	v_exp_f32_e32 v36, v36
	v_mul_f32_e32 v21, 0xbfb8aa3b, v21
	v_exp_f32_e32 v21, v21
	v_add_f32_e32 v20, 1.0, v20
	v_rcp_f32_e32 v52, v20
	v_add_f32_e32 v20, 1.0, v36
	global_load_dwordx4 v[100:103], v241, s[98:99]
	v_rcp_f32_e32 v75, v20
	v_add_f32_e32 v20, 1.0, v21
	v_add_f32_e32 v21, v38, v58
	v_mul_f32_e32 v21, 0xbfb8aa3b, v21
	v_add_f32_e32 v22, v22, v66
	v_exp_f32_e32 v21, v21
	v_mul_f32_e32 v22, 0xbfb8aa3b, v22
	v_exp_f32_e32 v22, v22
	v_rcp_f32_e32 v53, v20
	v_add_f32_e32 v20, 1.0, v21
	v_add_f32_e32 v21, v39, v59
	v_rcp_f32_e32 v84, v20
	v_add_f32_e32 v20, 1.0, v22
	v_mul_f32_e32 v21, 0xbfb8aa3b, v21
	v_add_f32_e32 v22, v23, v67
	v_exp_f32_e32 v21, v21
	v_mul_f32_e32 v22, 0xbfb8aa3b, v22
	v_exp_f32_e32 v22, v22
	v_rcp_f32_e32 v54, v20
	v_add_f32_e32 v20, 1.0, v21
	v_add_f32_e32 v21, v40, v60
	v_rcp_f32_e32 v85, v20
	v_add_f32_e32 v20, 1.0, v22
	v_mul_f32_e32 v21, 0xbfb8aa3b, v21
	s_waitcnt lgkmcnt(0)
	v_add_f32_e32 v22, v24, v68
	v_exp_f32_e32 v21, v21
	v_mul_f32_e32 v22, 0xbfb8aa3b, v22
	v_exp_f32_e32 v22, v22
	v_rcp_f32_e32 v55, v20
	v_add_f32_e32 v20, 1.0, v21
	v_add_f32_e32 v21, v41, v61
	v_rcp_f32_e32 v60, v20
	v_add_f32_e32 v20, 1.0, v22
	v_mul_f32_e32 v21, 0xbfb8aa3b, v21
	v_add_f32_e32 v22, v25, v69
	v_exp_f32_e32 v21, v21
	v_mul_f32_e32 v22, 0xbfb8aa3b, v22
	v_exp_f32_e32 v22, v22
	v_rcp_f32_e32 v56, v20
	global_load_dwordx4 v[108:111], v242, s[98:99]
	v_add_f32_e32 v20, 1.0, v21
	v_add_f32_e32 v21, v42, v62
	v_rcp_f32_e32 v61, v20
	v_add_f32_e32 v20, 1.0, v22
	v_mul_f32_e32 v21, 0xbfb8aa3b, v21
	v_add_f32_e32 v22, v26, v70
	v_exp_f32_e32 v21, v21
	v_mul_f32_e32 v22, 0xbfb8aa3b, v22
	v_exp_f32_e32 v22, v22
	v_rcp_f32_e32 v57, v20
	v_add_f32_e32 v20, 1.0, v21
	v_rcp_f32_e32 v62, v20
	v_add_f32_e32 v20, 1.0, v22
	v_rcp_f32_e32 v58, v20
	v_add_f32_e32 v20, v43, v63
	v_mul_f32_e32 v20, 0xbfb8aa3b, v20
	v_exp_f32_e32 v20, v20
	v_add_f32_e32 v21, v27, v71
	v_mul_f32_e32 v21, 0xbfb8aa3b, v21
	v_exp_f32_e32 v24, v21
	v_add_f32_e32 v25, 1.0, v20
	ds_read_b128 v[20:23], v2 offset:64
	v_rcp_f32_e32 v63, v25
	v_add_f32_e32 v59, 1.0, v24
	ds_read_b128 v[24:27], v3 offset:64
	ds_read_b128 v[36:39], v2 offset:96
	ds_read_b128 v[40:43], v3 offset:96
	s_waitcnt lgkmcnt(3)
	v_add_f32_e32 v2, v44, v20
	v_mul_f32_e32 v2, 0xbfb8aa3b, v2
	s_waitcnt lgkmcnt(2)
	v_add_f32_e32 v3, v28, v24
	v_exp_f32_e32 v2, v2
	v_mul_f32_e32 v3, 0xbfb8aa3b, v3
	v_exp_f32_e32 v3, v3
	s_waitcnt lgkmcnt(1)
	v_add_f32_e32 v28, v51, v39
	v_add_f32_e32 v2, 1.0, v2
	v_rcp_f32_e32 v20, v2
	v_add_f32_e32 v2, 1.0, v3
	global_load_dwordx4 v[104:107], v243, s[98:99]
	v_add_f32_e32 v3, v45, v21
	v_mul_f32_e32 v3, 0xbfb8aa3b, v3
	v_exp_f32_e32 v3, v3
	v_add_f32_e32 v21, v29, v25
	v_mul_f32_e32 v21, 0xbfb8aa3b, v21
	v_rcp_f32_e32 v64, v2
	v_add_f32_e32 v2, 1.0, v3
	v_add_f32_e32 v3, v46, v22
	v_exp_f32_e32 v24, v21
	v_mul_f32_e32 v3, 0xbfb8aa3b, v3
	v_exp_f32_e32 v3, v3
	v_add_f32_e32 v22, v30, v26
	v_mul_f32_e32 v22, 0xbfb8aa3b, v22
	v_rcp_f32_e32 v21, v2
	v_add_f32_e32 v2, 1.0, v24
	v_exp_f32_e32 v24, v22
	v_rcp_f32_e32 v65, v2
	v_add_f32_e32 v2, 1.0, v3
	v_add_f32_e32 v3, v47, v23
	v_mul_f32_e32 v3, 0xbfb8aa3b, v3
	v_add_f32_e32 v23, v31, v27
	v_exp_f32_e32 v3, v3
	v_mul_f32_e32 v23, 0xbfb8aa3b, v23
	v_rcp_f32_e32 v22, v2
	v_add_f32_e32 v2, 1.0, v24
	v_exp_f32_e32 v24, v23
	v_rcp_f32_e32 v66, v2
	v_add_f32_e32 v2, 1.0, v3
	v_add_f32_e32 v3, v48, v36
	v_rcp_f32_e32 v23, v2
	v_add_f32_e32 v2, 1.0, v24
	v_mul_f32_e32 v3, 0xbfb8aa3b, v3
	s_waitcnt lgkmcnt(0)
	v_add_f32_e32 v24, v32, v40
	v_exp_f32_e32 v3, v3
	v_mul_f32_e32 v24, 0xbfb8aa3b, v24
	v_exp_f32_e32 v25, v24
	v_rcp_f32_e32 v67, v2
	v_add_f32_e32 v2, 1.0, v3
	v_add_f32_e32 v3, v49, v37
	global_load_dwordx4 v[112:115], v241, s[98:99] offset:128
	v_rcp_f32_e32 v24, v2
	v_add_f32_e32 v2, 1.0, v25
	v_mul_f32_e32 v3, 0xbfb8aa3b, v3
	v_add_f32_e32 v25, v33, v41
	v_exp_f32_e32 v3, v3
	v_mul_f32_e32 v25, 0xbfb8aa3b, v25
	v_exp_f32_e32 v26, v25
	v_add_f32_e32 v27, v34, v42
	v_add_f32_e32 v3, 1.0, v3
	v_mul_f32_e32 v27, 0xbfb8aa3b, v27
	v_add_f32_e32 v29, v35, v43
	v_rcp_f32_e32 v25, v3
	v_add_f32_e32 v3, 1.0, v26
	v_add_f32_e32 v26, v50, v38
	v_exp_f32_e32 v27, v27
	v_mul_f32_e32 v28, 0xbfb8aa3b, v28
	v_mul_f32_e32 v29, 0xbfb8aa3b, v29
	v_mul_f32_e32 v26, 0xbfb8aa3b, v26
	v_exp_f32_e32 v28, v28
	v_exp_f32_e32 v29, v29
	v_exp_f32_e32 v26, v26
	v_add_f32_e32 v27, 1.0, v27
	v_pk_mul_f32 v[44:45], v[74:75], s[86:87] op_sel_hi:[1,0]
	v_pk_mul_f32 v[46:47], v[84:85], s[86:87] op_sel_hi:[1,0]
	v_rcp_f32_e32 v72, v27
	v_add_f32_e32 v27, 1.0, v28
	v_add_f32_e32 v73, 1.0, v29
	v_cvt_pk_bf16_f32 v28, v44, 0
	v_cvt_pk_bf16_f32 v29, v45, 0
	v_cvt_pk_bf16_f32 v32, v46, 0
	v_cvt_pk_bf16_f32 v33, v47, 0
	v_add_f32_e32 v26, 1.0, v26
	v_lshlrev_b32_e32 v29, 16, v29
	v_lshlrev_b32_e32 v28, 16, v28
	v_lshlrev_b32_e32 v33, 16, v33
	v_lshlrev_b32_e32 v32, 16, v32
	v_rcp_f32_e32 v26, v26
	v_rcp_f32_e32 v27, v27
	v_pk_fma_f32 v[30:31], v[74:75], s[86:87], v[28:29] op_sel_hi:[1,0,1] neg_lo:[0,0,1] neg_hi:[0,0,1]
	v_pk_fma_f32 v[34:35], v[84:85], s[86:87], v[32:33] op_sel_hi:[1,0,1] neg_lo:[0,0,1] neg_hi:[0,0,1]
	global_load_dwordx4 v[116:119], v242, s[98:99] offset:128
	v_pk_mul_f32 v[74:75], v[60:61], s[86:87] op_sel_hi:[1,0]
	v_pk_mul_f32 v[84:85], v[62:63], s[86:87] op_sel_hi:[1,0]
	v_cvt_pk_bf16_f32 v36, v74, 0
	v_cvt_pk_bf16_f32 v37, v75, 0
	v_cvt_pk_bf16_f32 v40, v84, 0
	v_cvt_pk_bf16_f32 v41, v85, 0
	v_lshlrev_b32_e32 v37, 16, v37
	v_lshlrev_b32_e32 v36, 16, v36
	v_lshlrev_b32_e32 v41, 16, v41
	v_lshlrev_b32_e32 v40, 16, v40
	v_pk_mul_f32 v[68:69], v[24:25], s[86:87] op_sel_hi:[1,0]
	v_pk_fma_f32 v[38:39], v[60:61], s[86:87], v[36:37] op_sel_hi:[1,0,1] neg_lo:[0,0,1] neg_hi:[0,0,1]
	v_pk_fma_f32 v[42:43], v[62:63], s[86:87], v[40:41] op_sel_hi:[1,0,1] neg_lo:[0,0,1] neg_hi:[0,0,1]
	v_pk_mul_f32 v[60:61], v[20:21], s[86:87] op_sel_hi:[1,0]
	v_pk_mul_f32 v[62:63], v[22:23], s[86:87] op_sel_hi:[1,0]
	v_cvt_pk_bf16_f32 v70, v68, 0
	v_cvt_pk_bf16_f32 v71, v69, 0
	v_cvt_pk_bf16_f32 v48, v60, 0
	v_cvt_pk_bf16_f32 v49, v61, 0
	v_cvt_pk_bf16_f32 v50, v62, 0
	v_cvt_pk_bf16_f32 v51, v63, 0
	v_lshlrev_b32_e32 v87, 16, v71
	v_lshlrev_b32_e32 v86, 16, v70
	v_pk_mul_f32 v[70:71], v[26:27], s[86:87] op_sel_hi:[1,0]
	v_lshlrev_b32_e32 v49, 16, v49
	v_lshlrev_b32_e32 v48, 16, v48
	v_lshlrev_b32_e32 v51, 16, v51
	v_lshlrev_b32_e32 v50, 16, v50
	v_cvt_pk_bf16_f32 v88, v70, 0
	v_cvt_pk_bf16_f32 v89, v71, 0
	v_pk_fma_f32 v[20:21], v[20:21], s[86:87], v[48:49] op_sel_hi:[1,0,1] neg_lo:[0,0,1] neg_hi:[0,0,1]
	v_pk_fma_f32 v[22:23], v[22:23], s[86:87], v[50:51] op_sel_hi:[1,0,1] neg_lo:[0,0,1] neg_hi:[0,0,1]
	v_pk_fma_f32 v[24:25], v[24:25], s[86:87], v[86:87] op_sel_hi:[1,0,1] neg_lo:[0,0,1] neg_hi:[0,0,1]
	v_lshlrev_b32_e32 v89, 16, v89
	v_lshlrev_b32_e32 v88, 16, v88
	v_cvt_pk_bf16_f32 v28, v28, v29
	v_cvt_pk_bf16_f32 v29, v32, v33
	v_cvt_pk_bf16_f32 v32, v36, v37
	v_cvt_pk_bf16_f32 v33, v40, v41
	v_add_u32_e32 v36, 0x9000, v1
	global_load_dwordx4 v[120:123], v243, s[98:99] offset:128
	ds_write2_b64 v36, v[28:29], v[32:33] offset1:2
	v_cvt_pk_bf16_f32 v28, v48, v49
	v_cvt_pk_bf16_f32 v29, v50, v51
	v_cvt_pk_bf16_f32 v32, v86, v87
	v_cvt_pk_bf16_f32 v33, v88, v89
	v_cvt_pk_bf16_f32 v20, v20, v21
	v_cvt_pk_bf16_f32 v21, v22, v23
	v_cvt_pk_bf16_f32 v22, v24, v25
	v_pk_fma_f32 v[24:25], v[26:27], s[86:87], v[88:89] op_sel_hi:[1,0,1] neg_lo:[0,0,1] neg_hi:[0,0,1]
	ds_write2_b64 v36, v[28:29], v[32:33] offset0:4 offset1:6
	v_cvt_pk_bf16_f32 v28, v30, v31
	v_cvt_pk_bf16_f32 v29, v34, v35
	v_cvt_pk_bf16_f32 v30, v38, v39
	v_cvt_pk_bf16_f32 v31, v42, v43
	v_add_u32_e32 v1, 0xb000, v1
	v_cvt_pk_bf16_f32 v23, v24, v25
	ds_write2_b64 v1, v[28:29], v[30:31] offset0:128 offset1:130
	ds_write2_b64 v1, v[20:21], v[22:23] offset0:132 offset1:134
	v_mov_b32_e32 v1, v180
	s_waitcnt lgkmcnt(0)
	s_barrier
	v_rcp_f32_e32 v59, v59
	v_add_u32_e32 v20, s42, v1
	v_ashrrev_i32_e32 v20, 3, v20
	v_cmp_gt_i32_e32 vcc, 32, v20
	v_lshlrev_b32_e32 v20, 8, v20
	v_lshlrev_b32_e32 v1, 5, v1
	v_cndmask_b32_e32 v21, v98, v99, vcc
	v_and_b32_e32 v20, 0x1f00, v20
	v_and_b32_e32 v1, 0xe0, v1
	v_add3_u32 v1, v21, v20, v1
	ds_write_b128 v1, v[76:79]
	ds_write_b128 v1, v[80:83] offset:16
	v_mov_b32_e32 v1, v180
	global_load_dwordx4 v[124:127], v244, s[98:99]
	v_rcp_f32_e32 v2, v2
	v_ashrrev_i32_e32 v24, 2, v1
	v_lshlrev_b32_e32 v22, 2, v1
	v_and_b32_e32 v20, 16, v1
	v_and_b32_e32 v148, -8, v24
	v_lshrrev_b32_e32 v21, 2, v1
	v_and_b32_e32 v22, 12, v22
	v_and_or_b32 v21, v21, 3, v148
	v_or3_b32 v20, v20, v22, s91
	v_lshlrev_b32_e32 v20, 1, v20
	v_mul_lo_u32 v21, v21, s64
	v_add3_u32 v25, s76, v20, v21
	ds_read_b64_tr_b16 v[20:21], v25 offset:36864
	ds_read_b64_tr_b16 v[22:23], v25 offset:37440
	ds_read_b64_tr_b16 v[36:37], v25 offset:39168
	ds_read_b64_tr_b16 v[38:39], v25 offset:39744
	ds_read_b64_tr_b16 v[40:41], v25 offset:41472
	ds_read_b64_tr_b16 v[42:43], v25 offset:42048
	ds_read_b64_tr_b16 v[48:49], v25 offset:43776
	ds_read_b64_tr_b16 v[50:51], v25 offset:44352
	ds_read_b64_tr_b16 v[76:77], v25 offset:46080
	ds_read_b64_tr_b16 v[78:79], v25 offset:46656
	ds_read_b64_tr_b16 v[80:81], v25 offset:48384
	ds_read_b64_tr_b16 v[82:83], v25 offset:48960
	ds_read_b64_tr_b16 v[86:87], v25 offset:50688
	ds_read_b64_tr_b16 v[88:89], v25 offset:51264
	global_load_dwordx4 v[128:131], v245, s[98:99]
	ds_read_b64_tr_b16 v[90:91], v25 offset:52992
	ds_read_b64_tr_b16 v[92:93], v25 offset:53568
	v_and_or_b32 v1, v1, 31, s43
	v_rcp_f32_e32 v3, v3
	v_rcp_f32_e32 v73, v73
	v_cmp_gt_i32_e32 vcc, v148, v1
	v_or_b32_e32 v24, 7, v24
	s_waitcnt lgkmcnt(0)
	s_barrier
	v_cndmask_b32_e64 v25, v224, 0, vcc
	v_cmp_lt_i32_e32 vcc, v148, v1
	s_add_i32 s27, 0, 0xd800
	s_add_i32 s30, 0, 0x1d400
	v_cndmask_b32_e32 v26, 0, v224, vcc
	v_perm_b32 v94, v26, v25, s65
	v_or_b32_e32 v26, 2, v148
	v_or_b32_e32 v25, 3, v148
	v_cmp_gt_i32_e32 vcc, v26, v1
	s_nop 1
	v_cndmask_b32_e64 v26, v224, 0, vcc
	v_cmp_gt_i32_e32 vcc, v25, v1
	s_nop 1
	v_cndmask_b32_e64 v25, v224, 0, vcc
	v_perm_b32 v95, v25, v26, s65
	v_or_b32_e32 v26, 4, v148
	v_or_b32_e32 v25, 5, v148
	v_cmp_gt_i32_e32 vcc, v26, v1
	s_nop 1
	v_cndmask_b32_e64 v26, v224, 0, vcc
	v_cmp_gt_i32_e32 vcc, v25, v1
	s_nop 1
	v_cndmask_b32_e64 v25, v224, 0, vcc
	v_perm_b32 v96, v25, v26, s65
	v_or_b32_e32 v25, 6, v148
	v_cmp_gt_i32_e32 vcc, v25, v1
	s_nop 1
	v_cndmask_b32_e64 v25, v224, 0, vcc
	global_load_dwordx4 v[132:135], v246, s[98:99]
	v_cmp_gt_i32_e32 vcc, v24, v1
	s_nop 1
	v_cndmask_b32_e64 v24, v224, 0, vcc
	v_perm_b32 v97, v24, v25, s65
	s_waitcnt lgkmcnt(14)
	s_nop 0
	v_mfma_f32_32x32x16_bf16 v[20:35], v[20:23], v[94:97], 0
	s_waitcnt lgkmcnt(6)
	v_mfma_f32_32x32x16_bf16 v[20:35], v[76:79], v[94:97], v[20:35]
	v_add_u32_e32 v76, 16, v148
	v_cmp_gt_i32_e32 vcc, v76, v1
	v_add_u32_e32 v77, 17, v148
	v_add_u32_e32 v78, 18, v148
	v_cndmask_b32_e64 v76, v224, 0, vcc
	v_cmp_gt_i32_e32 vcc, v77, v1
	v_add_u32_e32 v79, 20, v148
	v_add_u32_e32 v96, 22, v148
	v_cndmask_b32_e64 v94, v224, 0, vcc
	v_cmp_gt_i32_e32 vcc, v78, v1
	v_add_u32_e32 v78, 19, v148
	v_perm_b32 v76, v94, v76, s65
	v_cndmask_b32_e64 v77, v224, 0, vcc
	v_cmp_gt_i32_e32 vcc, v78, v1
	s_nop 1
	v_cndmask_b32_e64 v95, v224, 0, vcc
	v_cmp_gt_i32_e32 vcc, v79, v1
	v_add_u32_e32 v79, 21, v148
	v_perm_b32 v77, v95, v77, s65
	v_cndmask_b32_e64 v78, v224, 0, vcc
	v_cmp_gt_i32_e32 vcc, v79, v1
	s_nop 1
	v_cndmask_b32_e64 v97, v224, 0, vcc
	v_cmp_gt_i32_e32 vcc, v96, v1
	v_add_u32_e32 v96, 23, v148
	v_perm_b32 v78, v97, v78, s65
	v_cndmask_b32_e64 v79, v224, 0, vcc
	v_cmp_gt_i32_e32 vcc, v96, v1
	s_nop 1
	v_cndmask_b32_e64 v96, v224, 0, vcc
	v_perm_b32 v79, v96, v79, s65
	s_nop 1
	v_mfma_f32_32x32x16_bf16 v[20:35], v[36:39], v[76:79], v[20:35]
	v_add_u32_e32 v36, 32, v148
	v_cmp_gt_i32_e32 vcc, v36, v1
	v_add_u32_e32 v37, 33, v148
	v_add_u32_e32 v38, 34, v148
	v_cndmask_b32_e64 v36, v224, 0, vcc
	v_cmp_gt_i32_e32 vcc, v37, v1
	v_add_u32_e32 v39, 36, v148
	s_waitcnt lgkmcnt(4)
	v_mfma_f32_32x32x16_bf16 v[20:35], v[80:83], v[76:79], v[20:35]
	v_cndmask_b32_e64 v76, v224, 0, vcc
	v_cmp_gt_i32_e32 vcc, v38, v1
	v_add_u32_e32 v38, 35, v148
	v_add_u32_e32 v78, 38, v148
	v_cndmask_b32_e64 v37, v224, 0, vcc
	v_cmp_gt_i32_e32 vcc, v38, v1
	v_perm_b32 v36, v76, v36, s65
	v_mov_b32_e32 v81, v180
	v_cndmask_b32_e64 v77, v224, 0, vcc
	v_cmp_gt_i32_e32 vcc, v39, v1
	v_add_u32_e32 v39, 37, v148
	v_perm_b32 v37, v77, v37, s65
	v_cndmask_b32_e64 v38, v224, 0, vcc
	v_cmp_gt_i32_e32 vcc, v39, v1
	s_nop 1
	v_cndmask_b32_e64 v79, v224, 0, vcc
	v_cmp_gt_i32_e32 vcc, v78, v1
	v_add_u32_e32 v78, 39, v148
	v_perm_b32 v38, v79, v38, s65
	v_cndmask_b32_e64 v39, v224, 0, vcc
	v_cmp_gt_i32_e32 vcc, v78, v1
	s_nop 1
	v_cndmask_b32_e64 v78, v224, 0, vcc
	v_perm_b32 v39, v78, v39, s65
	s_nop 1
	v_mfma_f32_32x32x16_bf16 v[20:35], v[40:43], v[36:39], v[20:35]
	v_add_u32_e32 v42, 54, v148
	global_load_dwordx4 v[136:139], v247, s[98:99]
	s_waitcnt lgkmcnt(2)
	v_mfma_f32_32x32x16_bf16 v[20:35], v[86:89], v[36:39], v[20:35]
	v_add_u32_e32 v36, 48, v148
	v_cmp_gt_i32_e32 vcc, v36, v1
	v_add_u32_e32 v37, 49, v148
	v_add_u32_e32 v38, 50, v148
	v_cndmask_b32_e64 v36, v224, 0, vcc
	v_cmp_gt_i32_e32 vcc, v37, v1
	v_add_u32_e32 v39, 52, v148
	v_and_b32_e32 v89, 31, v81
	v_cndmask_b32_e64 v40, v224, 0, vcc
	v_cmp_gt_i32_e32 vcc, v38, v1
	v_add_u32_e32 v38, 51, v148
	v_perm_b32 v36, v40, v36, s65
	v_cndmask_b32_e64 v37, v224, 0, vcc
	v_cmp_gt_i32_e32 vcc, v38, v1
	v_ashrrev_i32_e32 v88, 5, v81
	v_lshl_add_u32 v178, v88, 2, s91
	v_cndmask_b32_e64 v41, v224, 0, vcc
	v_cmp_gt_i32_e32 vcc, v39, v1
	v_add_u32_e32 v39, 53, v148
	v_perm_b32 v37, v41, v37, s65
	v_cndmask_b32_e64 v38, v224, 0, vcc
	v_cmp_gt_i32_e32 vcc, v39, v1
	v_lshlrev_b32_e32 v40, 2, v178
	v_add_u32_e32 v185, 16, v178
	v_cndmask_b32_e64 v43, v224, 0, vcc
	v_cmp_gt_i32_e32 vcc, v42, v1
	v_add_u32_e32 v42, 55, v148
	v_perm_b32 v38, v43, v38, s65
	v_cndmask_b32_e64 v39, v224, 0, vcc
	v_cmp_gt_i32_e32 vcc, v42, v1
	v_add_u32_e32 v189, 24, v178
	s_nop 0
	v_cndmask_b32_e64 v1, v224, 0, vcc
	v_perm_b32 v39, v1, v39, s65
	v_bitop3_b32 v1, v89, 63, s43 bitop3:0x36
	s_nop 0
	v_mfma_f32_32x32x16_bf16 v[20:35], v[48:51], v[36:39], v[20:35]
	s_waitcnt lgkmcnt(0)
	v_mfma_f32_32x32x16_bf16 v[20:35], v[90:93], v[36:39], v[20:35]
	v_or_b32_e32 v36, s43, v89
	v_cndmask_b32_e64 v1, v1, v36, s[36:37]
	v_lshl_add_u32 v37, v1, 2, 0
	v_add_u32_e32 v37, 0x24000, v37
	ds_read_b32 v80, v37
	v_mov_b32_e32 v37, s30
	v_mov_b32_e32 v38, s27
	v_cmp_gt_u32_e32 vcc, 32, v1
	v_mul_u32_u24_e32 v188, 0x90, v36
	s_nop 2
	v_sub_f32_e32 v87, v23, v47
	v_cndmask_b32_e32 v37, v37, v38, vcc
	v_lshlrev_b32_e32 v38, 8, v1
	v_and_b32_e32 v38, 0x1f00, v38
	v_add_u32_e32 v179, v37, v38
	v_cndmask_b32_e32 v37, v98, v99, vcc
	v_add_u32_e32 v181, v37, v38
	v_add_u32_e32 v36, v179, v40
	v_add_u32_e32 v41, v181, v40
	v_add_u32_e32 v40, 0, v40
	ds_read_b128 v[48:51], v41
	v_add_u32_e32 v182, 0x24700, v40
	ds_read_b128 v[36:39], v36
	v_add_u32_e32 v183, 0x24800, v40
	ds_read_b128 v[76:79], v182
	ds_read_b128 v[90:93], v183
	v_sub_f32_e32 v47, v22, v46
	v_sub_f32_e32 v46, v21, v45
	v_sub_f32_e32 v45, v20, v44
	v_exp_f32_e32 v44, v20
	v_exp_f32_e32 v82, v45
	v_exp_f32_e64 v20, -v20
	v_exp_f32_e32 v45, v21
	v_exp_f32_e32 v83, v46
	v_exp_f32_e64 v21, -v21
	v_exp_f32_e32 v46, v22
	v_exp_f32_e32 v86, v47
	v_exp_f32_e32 v47, v23
	v_exp_f32_e32 v87, v87
	global_load_dwordx4 v[140:143], v248, s[98:99]
	s_waitcnt lgkmcnt(1)
	v_pk_mul_f32 v[78:79], v[50:51], v[78:79]
	v_pk_mul_f32 v[76:77], v[48:49], v[76:77]
	v_exp_f32_e64 v22, -v22
	v_exp_f32_e64 v23, -v23
	v_pk_mul_f32 v[94:95], v[80:81], v[78:79] op_sel_hi:[0,1]
	v_pk_mul_f32 v[96:97], v[80:81], v[76:77] op_sel_hi:[0,1]
	v_pk_add_f32 v[76:77], v[54:55], -1.0 op_sel_hi:[1,0]
	v_pk_add_f32 v[78:79], v[52:53], -1.0 op_sel_hi:[1,0]
	s_waitcnt lgkmcnt(0)
	v_pk_fma_f32 v[76:77], v[76:77], v[92:93], 1.0 op_sel_hi:[1,1,0]
	v_pk_fma_f32 v[78:79], v[78:79], v[90:91], 1.0 op_sel_hi:[1,1,0]
	v_pk_mul_f32 v[76:77], v[50:51], v[76:77]
	v_pk_mul_f32 v[78:79], v[48:49], v[78:79]
	v_pk_mul_f32 v[50:51], v[52:53], v[96:97]
	v_pk_mul_f32 v[148:149], v[38:39], v[46:47]
	v_pk_mul_f32 v[154:155], v[36:37], v[44:45]
	v_pk_mul_f32 v[48:49], v[54:55], v[94:95]
	v_pk_mul_f32 v[152:153], v[20:21], v[78:79]
	v_pk_mul_f32 v[52:53], v[86:87], v[94:95]
	v_pk_mul_f32 v[54:55], v[82:83], v[96:97]
	v_pk_mul_f32 v[20:21], v[20:21], v[50:51]
	v_lshlrev_b32_e32 v50, 1, v178
	v_add_u32_e32 v184, 0x24900, v40
	v_pk_mul_f32 v[150:151], v[22:23], v[76:77]
	v_pk_mul_f32 v[22:23], v[22:23], v[48:49]
	v_cvt_pk_bf16_f32 v48, v54, v55
	v_cvt_pk_bf16_f32 v49, v52, v53
	v_add3_u32 v52, v50, v188, s76
	v_cvt_pk_bf16_f32 v50, v154, v155
	v_cvt_pk_bf16_f32 v51, v148, v149
	v_add_u32_e32 v98, 8, v178
	ds_read_b128 v[40:43], v184
	ds_write2st64_b64 v52, v[48:49], v[50:51] offset1:18
	v_cvt_pk_bf16_f32 v20, v20, v21
	v_cvt_pk_bf16_f32 v21, v22, v23
	v_cvt_pk_bf16_f32 v22, v152, v153
	v_cvt_pk_bf16_f32 v23, v150, v151
	v_lshlrev_b32_e32 v48, 2, v98
	ds_write2st64_b64 v52, v[20:21], v[22:23] offset0:36 offset1:54
	v_add_u32_e32 v20, v179, v48
	v_add_u32_e32 v48, v181, v48
	ds_read_b128 v[20:23], v20
	ds_read_b128 v[90:93], v48
	ds_read_b128 v[94:97], v182 offset:32
	ds_read_b128 v[156:159], v183 offset:32
	ds_read_b128 v[48:51], v184 offset:32
	v_sub_f32_e32 v82, v27, v85
	v_sub_f32_e32 v55, v26, v84
	v_sub_f32_e32 v54, v25, v75
	v_sub_f32_e32 v53, v24, v74
	v_exp_f32_e32 v52, v24
	v_exp_f32_e32 v84, v53
	v_exp_f32_e32 v53, v25
	v_exp_f32_e32 v85, v54
	v_exp_f32_e32 v54, v26
	v_exp_f32_e32 v86, v55
	v_exp_f32_e64 v26, -v26
	v_exp_f32_e32 v55, v27
	v_exp_f32_e32 v87, v82
	v_exp_f32_e64 v27, -v27
	s_waitcnt lgkmcnt(2)
	v_pk_mul_f32 v[74:75], v[92:93], v[96:97]
	v_exp_f32_e64 v24, -v24
	v_exp_f32_e64 v25, -v25
	v_pk_mul_f32 v[82:83], v[90:91], v[94:95]
	v_pk_mul_f32 v[94:95], v[80:81], v[74:75] op_sel_hi:[0,1]
	v_pk_add_f32 v[74:75], v[58:59], -1.0 op_sel_hi:[1,0]
	v_pk_mul_f32 v[96:97], v[80:81], v[82:83] op_sel_hi:[0,1]
	v_pk_add_f32 v[82:83], v[56:57], -1.0 op_sel_hi:[1,0]
	s_waitcnt lgkmcnt(1)
	v_pk_fma_f32 v[74:75], v[74:75], v[158:159], 1.0 op_sel_hi:[1,1,0]
	v_pk_fma_f32 v[82:83], v[82:83], v[156:157], 1.0 op_sel_hi:[1,1,0]
	v_pk_mul_f32 v[74:75], v[92:93], v[74:75]
	v_pk_mul_f32 v[58:59], v[58:59], v[94:95]
	v_pk_mul_f32 v[82:83], v[90:91], v[82:83]
	v_pk_mul_f32 v[158:159], v[54:55], v[22:23]
	v_pk_mul_f32 v[164:165], v[52:53], v[20:21]
	v_pk_mul_f32 v[56:57], v[56:57], v[96:97]
	v_pk_mul_f32 v[156:157], v[26:27], v[74:75]
	v_pk_mul_f32 v[86:87], v[86:87], v[94:95]
	v_pk_mul_f32 v[84:85], v[84:85], v[96:97]
	v_pk_mul_f32 v[26:27], v[26:27], v[58:59]
	v_lshlrev_b32_e32 v58, 1, v98
	v_pk_mul_f32 v[166:167], v[24:25], v[82:83]
	v_pk_mul_f32 v[24:25], v[24:25], v[56:57]
	v_cvt_pk_bf16_f32 v56, v84, v85
	v_cvt_pk_bf16_f32 v57, v86, v87
	v_add3_u32 v84, v58, v188, s76
	v_cvt_pk_bf16_f32 v58, v164, v165
	v_cvt_pk_bf16_f32 v59, v158, v159
	ds_write2st64_b64 v84, v[56:57], v[58:59] offset1:18
	v_cvt_pk_bf16_f32 v24, v24, v25
	v_cvt_pk_bf16_f32 v25, v26, v27
	v_cvt_pk_bf16_f32 v26, v166, v167
	v_cvt_pk_bf16_f32 v27, v156, v157
	v_lshlrev_b32_e32 v56, 2, v185
	ds_write2st64_b64 v84, v[24:25], v[26:27] offset0:36 offset1:54
	v_add_u32_e32 v24, v179, v56
	v_add_u32_e32 v56, v181, v56
	global_load_dwordx4 v[144:147], v249, s[98:99]
	ds_read_b128 v[24:27], v24
	ds_read_b128 v[90:93], v56
	ds_read_b128 v[84:87], v182 offset:64
	ds_read_b128 v[94:97], v183 offset:64
	ds_read_b128 v[56:59], v184 offset:64
	v_sub_f32_e32 v160, v31, v63
	v_sub_f32_e32 v63, v30, v62
	v_sub_f32_e32 v62, v29, v61
	v_sub_f32_e32 v61, v28, v60
	v_exp_f32_e32 v60, v28
	v_exp_f32_e32 v98, v61
	v_exp_f32_e32 v61, v29
	v_exp_f32_e32 v99, v62
	v_exp_f32_e32 v62, v30
	v_exp_f32_e32 v168, v63
	v_exp_f32_e64 v30, -v30
	v_exp_f32_e32 v63, v31
	v_exp_f32_e32 v169, v160
	v_exp_f32_e64 v31, -v31
	s_waitcnt lgkmcnt(2)
	v_pk_mul_f32 v[84:85], v[90:91], v[84:85]
	v_exp_f32_e64 v28, -v28
	v_exp_f32_e64 v29, -v29
	v_pk_mul_f32 v[86:87], v[92:93], v[86:87]
	v_pk_mul_f32 v[176:177], v[80:81], v[84:85] op_sel_hi:[0,1]
	v_pk_add_f32 v[84:85], v[66:67], -1.0 op_sel_hi:[1,0]
	v_pk_mul_f32 v[172:173], v[80:81], v[86:87] op_sel_hi:[0,1]
	v_pk_add_f32 v[86:87], v[64:65], -1.0 op_sel_hi:[1,0]
	s_waitcnt lgkmcnt(1)
	v_pk_fma_f32 v[84:85], v[84:85], v[96:97], 1.0 op_sel_hi:[1,1,0]
	v_pk_fma_f32 v[86:87], v[86:87], v[94:95], 1.0 op_sel_hi:[1,1,0]
	v_pk_mul_f32 v[84:85], v[92:93], v[84:85]
	v_pk_mul_f32 v[66:67], v[66:67], v[172:173]
	v_pk_mul_f32 v[86:87], v[90:91], v[86:87]
	v_pk_mul_f32 v[160:161], v[62:63], v[26:27]
	v_pk_mul_f32 v[174:175], v[60:61], v[24:25]
	v_pk_mul_f32 v[64:65], v[64:65], v[176:177]
	v_pk_mul_f32 v[162:163], v[30:31], v[84:85]
	v_pk_mul_f32 v[90:91], v[168:169], v[172:173]
	v_pk_mul_f32 v[92:93], v[98:99], v[176:177]
	v_pk_mul_f32 v[30:31], v[30:31], v[66:67]
	v_lshlrev_b32_e32 v66, 1, v185
	v_pk_mul_f32 v[170:171], v[28:29], v[86:87]
	v_pk_mul_f32 v[28:29], v[28:29], v[64:65]
	v_cvt_pk_bf16_f32 v64, v92, v93
	v_cvt_pk_bf16_f32 v65, v90, v91
	v_add3_u32 v90, v66, v188, s76
	v_cvt_pk_bf16_f32 v66, v174, v175
	v_cvt_pk_bf16_f32 v67, v160, v161
	ds_write2st64_b64 v90, v[64:65], v[66:67] offset1:18
	v_cvt_pk_bf16_f32 v28, v28, v29
	v_cvt_pk_bf16_f32 v29, v30, v31
	v_cvt_pk_bf16_f32 v30, v170, v171
	v_cvt_pk_bf16_f32 v31, v162, v163
	v_lshlrev_b32_e32 v64, 2, v189
	ds_write2st64_b64 v90, v[28:29], v[30:31] offset0:36 offset1:54
	v_add_u32_e32 v28, v179, v64
	v_add_u32_e32 v64, v181, v64
	ds_read_b128 v[28:31], v28
	ds_read_b128 v[90:93], v64
	ds_read_b128 v[94:97], v182 offset:96
	ds_read_b128 v[176:179], v183 offset:96
	ds_read_b128 v[64:67], v184 offset:96
	v_sub_f32_e32 v168, v35, v71
	v_sub_f32_e32 v71, v34, v70
	v_sub_f32_e32 v70, v33, v69
	v_sub_f32_e32 v69, v32, v68
	v_exp_f32_e32 v68, v32
	v_exp_f32_e32 v98, v69
	v_exp_f32_e64 v182, -v32
	v_exp_f32_e32 v69, v33
	v_exp_f32_e32 v99, v70
	v_exp_f32_e64 v183, -v33
	v_exp_f32_e32 v70, v34
	v_exp_f32_e32 v184, v71
	v_exp_f32_e64 v186, -v34
	v_exp_f32_e32 v71, v35
	v_exp_f32_e32 v185, v168
	v_exp_f32_e64 v187, -v35
	s_waitcnt lgkmcnt(2)
	v_pk_mul_f32 v[32:33], v[92:93], v[96:97]
	v_pk_mul_f32 v[34:35], v[90:91], v[94:95]
	v_pk_mul_f32 v[94:95], v[80:81], v[32:33] op_sel_hi:[0,1]
	v_pk_mul_f32 v[96:97], v[80:81], v[34:35] op_sel_hi:[0,1]
	v_pk_add_f32 v[32:33], v[72:73], -1.0 op_sel_hi:[1,0]
	v_pk_add_f32 v[34:35], v[2:3], -1.0 op_sel_hi:[1,0]
	s_waitcnt lgkmcnt(1)
	v_pk_fma_f32 v[32:33], v[32:33], v[178:179], 1.0 op_sel_hi:[1,1,0]
	v_pk_fma_f32 v[34:35], v[34:35], v[176:177], 1.0 op_sel_hi:[1,1,0]
	v_pk_mul_f32 v[32:33], v[92:93], v[32:33]
	v_pk_mul_f32 v[34:35], v[90:91], v[34:35]
	v_pk_mul_f32 v[72:73], v[72:73], v[94:95]
	v_pk_mul_f32 v[2:3], v[2:3], v[96:97]
	v_pk_mul_f32 v[172:173], v[70:71], v[30:31]
	v_pk_mul_f32 v[176:177], v[68:69], v[28:29]
	v_pk_mul_f32 v[168:169], v[186:187], v[32:33]
	v_pk_mul_f32 v[178:179], v[182:183], v[34:35]
	v_pk_mul_f32 v[90:91], v[184:185], v[94:95]
	v_pk_mul_f32 v[92:93], v[98:99], v[96:97]
	v_pk_mul_f32 v[72:73], v[186:187], v[72:73]
	v_pk_mul_f32 v[2:3], v[182:183], v[2:3]
	v_lshlrev_b32_e32 v80, 1, v189
	v_cmp_eq_u32_e32 vcc, 31, v89
	v_cvt_pk_bf16_f32 v92, v92, v93
	v_cvt_pk_bf16_f32 v93, v90, v91
	v_add3_u32 v80, v80, v188, s76
	v_cvt_pk_bf16_f32 v90, v176, v177
	v_cvt_pk_bf16_f32 v91, v172, v173
	v_cvt_pk_bf16_f32 v2, v2, v3
	v_cvt_pk_bf16_f32 v3, v72, v73
	v_cvt_pk_bf16_f32 v72, v178, v179
	v_cvt_pk_bf16_f32 v73, v168, v169
	s_and_b64 s[38:39], s[62:63], vcc
	ds_write2st64_b64 v80, v[92:93], v[90:91] offset1:18
	ds_write2st64_b64 v80, v[2:3], v[72:73] offset0:36 offset1:54
	s_and_saveexec_b64 s[30:31], s[38:39]
	s_cbranch_execz .LBB0_85
	v_readlane_b32 s27, v255, 10
	s_nop 1
	v_lshl_add_u32 v2, v88, 4, s27
	ds_write_b128 v2, v[44:47]
	ds_write_b128 v2, v[52:55] offset:32
	ds_write_b128 v2, v[60:63] offset:64
	ds_write_b128 v2, v[68:71] offset:96

.LBB0_87:
	s_or_b64 exec, exec, s[30:31]
	s_add_i32 s27, s50, 16
	v_readlane_b32 s30, v252, 21
	s_cmp_ge_u32 s27, s30
	s_cselect_b64 s[30:31], -1, 0
	s_and_b64 vcc, exec, s[30:31]
.LBB0_105:
	s_waitcnt lgkmcnt(0)
	s_barrier
	v_mov_b32_e32 v2, v180
	s_lshr_b32 s68, s50, 6
	v_cmp_lt_u32_e32 vcc, 31, v2
	s_or_b64 s[38:39], s[96:97], vcc
	s_and_saveexec_b64 vcc, s[38:39]
	s_xor_b64 s[38:39], exec, vcc
	s_lshl_b32 s57, s68, 12
	s_or_saveexec_b64 s[38:39], s[38:39]
	s_and_b32 s50, s50, 63
	s_lshl_b32 s56, s50, 6
	v_mov_b32_e32 v1, s57
	s_xor_b64 exec, exec, s[38:39]
	s_cbranch_execz .LBB0_109
	v_or_b32_e32 v1, s43, v2
	v_bitop3_b32 v2, v2, 63, s43 bitop3:0x36
	v_cndmask_b32_e64 v1, v2, v1, s[36:37]
	v_readlane_b32 s40, v255, 11
	v_mov_b32_e32 v21, v0
	v_readlane_b32 vcc_lo, v255, 13
	v_lshl_add_u32 v2, v1, 2, s40
	s_waitcnt lgkmcnt(0)
	ds_read2st64_b32 v[2:3], v2 offset1:1
	s_lshl_b32 s40, s68, 12
	s_or_b32 s41, s40, s56
	v_or_b32_e32 v20, s41, v1
	v_readlane_b32 vcc_hi, v255, 14
	s_waitcnt lgkmcnt(0)
	v_add_f32_e32 v1, v2, v3
	v_lshlrev_b64 v[2:3], 5, v[20:21]
	v_lshl_add_u64 v[2:3], vcc, 0, v[2:3]
	global_store_dword v[2:3], v1, off
	v_mov_b32_e32 v1, s40

	.amdhsa_kernel _Z6mk_fwd4Args
		.amdhsa_group_segment_fixed_size 0
		.amdhsa_private_segment_fixed_size 0
		.amdhsa_kernarg_size 440
		.amdhsa_user_sgpr_count 2
		.amdhsa_user_sgpr_dispatch_ptr 0
		.amdhsa_user_sgpr_queue_ptr 0
		.amdhsa_user_sgpr_kernarg_segment_ptr 1
		.amdhsa_user_sgpr_dispatch_id 0
		.amdhsa_user_sgpr_kernarg_preload_length 0
		.amdhsa_user_sgpr_kernarg_preload_offset 0
		.amdhsa_user_sgpr_private_segment_size 0
		.amdhsa_uses_dynamic_stack 0
		.amdhsa_enable_private_segment 0
		.amdhsa_system_sgpr_workgroup_id_x 1
		.amdhsa_system_sgpr_workgroup_id_y 0
		.amdhsa_system_sgpr_workgroup_id_z 0
		.amdhsa_system_sgpr_workgroup_info 0
		.amdhsa_system_vgpr_workitem_id 0
		.amdhsa_next_free_vgpr 256
		.amdhsa_next_free_sgpr 102
		.amdhsa_accum_offset 256
		.amdhsa_reserve_vcc 1
		.amdhsa_float_round_mode_32 0
		.amdhsa_float_round_mode_16_64 0
		.amdhsa_float_denorm_mode_32 3
		.amdhsa_float_denorm_mode_16_64 3
		.amdhsa_dx10_clamp 1
		.amdhsa_ieee_mode 1
		.amdhsa_fp16_overflow 0
		.amdhsa_tg_split 0
		.amdhsa_exception_fp_ieee_invalid_op 0
		.amdhsa_exception_fp_denorm_src 0
		.amdhsa_exception_fp_ieee_div_zero 0
		.amdhsa_exception_fp_ieee_overflow 0
		.amdhsa_exception_fp_ieee_underflow 0
		.amdhsa_exception_fp_ieee_inexact 0
		.amdhsa_exception_int_div_zero 0
	.end_amdhsa_kernel

amdhsa.kernels:
  - .agpr_count:     0
    .args:
      - .offset:         0
        .size:           184
        .value_kind:     by_value
      - .offset:         184
        .size:           4
        .value_kind:     hidden_block_count_x
      - .offset:         188
        .size:           4
        .value_kind:     hidden_block_count_y
      - .offset:         192
        .size:           4
        .value_kind:     hidden_block_count_z
      - .offset:         196
        .size:           2
        .value_kind:     hidden_group_size_x
      - .offset:         198
        .size:           2
        .value_kind:     hidden_group_size_y
      - .offset:         200
        .size:           2
        .value_kind:     hidden_group_size_z
      - .offset:         202
        .size:           2
        .value_kind:     hidden_remainder_x
      - .offset:         204
        .size:           2
        .value_kind:     hidden_remainder_y
      - .offset:         206
        .size:           2
        .value_kind:     hidden_remainder_z
      - .offset:         224
        .size:           8
        .value_kind:     hidden_global_offset_x
      - .offset:         232
        .size:           8
        .value_kind:     hidden_global_offset_y
      - .offset:         240
        .size:           8
        .value_kind:     hidden_global_offset_z
      - .offset:         248
        .size:           2
        .value_kind:     hidden_grid_dims
      - .offset:         304
        .size:           4
        .value_kind:     hidden_dynamic_lds_size
    .group_segment_fixed_size: 0
    .kernarg_segment_align: 8
    .kernarg_segment_size: 440
    .language:       OpenCL C
    .language_version:
      - 2
      - 0
    .max_flat_workgroup_size: 512
    .name:           _Z6mk_fwd4Args
    .private_segment_fixed_size: 0
    .sgpr_count:     108
    .sgpr_spill_count: 229
    .symbol:         _Z6mk_fwd4Args.kd
    .uniform_work_group_size: 1
    .uses_dynamic_stack: false
    .vgpr_count:     256
    .vgpr_spill_count: 0
    .wavefront_size: 64
